# attention PV: 16 V-fragment ds_reads batched with counted lgkmcnt (loop body + peeled last step)
# speedup vs baseline: 1.0129x; 1.0048x over previous
; #define LAS __attribute__((address_space(3)))
; __device__ __forceinline__ unsigned cvt_pk_bf16(float lo, float hi) { unsigned r; asm volatile("v_cvt_pk_bf16_f32 %0, %1, %2" : "=v"(r) : "v"(lo), "v"(hi)); return r; }
; #define MFMA16(a, b, c) __builtin_amdgcn_mfma_f32_16x16x32_bf16((a), (b), (c), 0, 0, 0)
; __device__ __forceinline__ int att_fv(int dh) { return (dh >> 1) & 7; }
; __device__ __forceinline__ void attn_phase(const bf16_t* Q, const bf16_t* Kb, const bf16_t* VTa, const float* rpb, bf16_t* Y, LAS unsigned char* lds, int bx, int G, int tid, int wave, int lane) {
;     ...
;             f32x4 o[4];
; #pragma unroll
;             for (int dt = 0; dt < 4; ++dt) o[dt] = (f32x4){0.f, 0.f, 0.f, 0.f};
; #pragma unroll
;             for (int ii = 0; ii < 4; ++ii) {
;                 const int i = 4 * hf + ii;
; #pragma unroll
;                 for (int dt = 0; dt < 4; ++dt) { const int dh = 16 * dt + fr;
;                     const bf16x8 vf = *(const LAS bf16x8*)(VL + ((rs + i) & 7) * 8192 + dh * 128 + ((((cs >> 3) + fq) ^ att_fv(dh)) << 4));
;                     o[dt] = MFMA16(vf, pb[ii], o[dt]); }
;             }
;             LAS float* ml = (LAS float*)(lds + 131072 + 2048) + (size_t)(g * 64 + lane) * 2;
;             LAS u32x2* ol = (LAS u32x2*)(lds + 131072 + 4096) + (size_t)(g * 64 + lane) * 4;
;             if (hf == 1) {
; #pragma unroll
;                 for (int dt = 0; dt < 4; ++dt) { u32x2 w; w.x = cvt_pk_bf16(o[dt][0], o[dt][1]); w.y = cvt_pk_bf16(o[dt][2], o[dt][3]); ol[dt] = w; }
;                 ml[0] = mx; ml[1] = l;
.LBB0_457:
	s_add_i32 s31, s64, s87
	s_lshl_b32 s31, s31, 13
	s_and_b32 s56, s31, 0xe000
	s_waitcnt lgkmcnt(0)
	s_barrier
	v_add_u32_e32 v35, s56, v49
	s_waitcnt lgkmcnt(0)
	v_add_f32_e32 v33, v22, v23
	s_add_i32 s56, s31, 0x2000
	s_and_b32 s56, s56, 0xe000
	v_add_u32_e32 v36, s56, v49
	s_add_i32 s56, s31, 0x4000
	s_and_b32 s56, s56, 0xe000
	v_add_u32_e32 v37, s56, v49
	s_addk_i32 s31, 0x6000
	s_and_b32 s31, s31, 0xe000
	v_add_u32_e32 v63, s31, v49
	s_andn2_b64 vcc, exec, s[36:37]
	ds_read_b128 v[100:103], v35
	ds_read_b128 v[104:107], v35 offset:2048
	ds_read_b128 v[108:111], v35 offset:4096
	ds_read_b128 v[112:115], v35 offset:6144
	ds_read_b128 v[116:119], v36
	ds_read_b128 v[120:123], v36 offset:2048
	ds_read_b128 v[124:127], v36 offset:4096
	ds_read_b128 v[128:131], v36 offset:6144
	ds_read_b128 v[132:135], v37
	ds_read_b128 v[136:139], v37 offset:2048
	ds_read_b128 v[140:143], v37 offset:4096
	ds_read_b128 v[144:147], v37 offset:6144
	ds_read_b128 v[148:151], v63
	ds_read_b128 v[152:155], v63 offset:2048
	ds_read_b128 v[156:159], v63 offset:4096
	ds_read_b128 v[174:177], v63 offset:6144
	s_waitcnt lgkmcnt(12)
	v_mfma_f32_16x16x32_bf16 v[22:25], v[100:103], v[10:13], 0
	v_mfma_f32_16x16x32_bf16 v[178:181], v[104:107], v[10:13], 0
	v_mfma_f32_16x16x32_bf16 v[182:185], v[108:111], v[10:13], 0
	v_mfma_f32_16x16x32_bf16 v[10:13], v[112:115], v[10:13], 0
	s_waitcnt lgkmcnt(8)
	v_mfma_f32_16x16x32_bf16 v[22:25], v[116:119], v[14:17], v[22:25]
	v_mfma_f32_16x16x32_bf16 v[178:181], v[120:123], v[14:17], v[178:181]
	v_mfma_f32_16x16x32_bf16 v[182:185], v[124:127], v[14:17], v[182:185]
	v_mfma_f32_16x16x32_bf16 v[10:13], v[128:131], v[14:17], v[10:13]
	s_waitcnt lgkmcnt(4)
	v_mfma_f32_16x16x32_bf16 v[22:25], v[132:135], v[18:21], v[22:25]
	v_mfma_f32_16x16x32_bf16 v[178:181], v[136:139], v[18:21], v[178:181]
	v_mfma_f32_16x16x32_bf16 v[182:185], v[140:143], v[18:21], v[182:185]
	v_mfma_f32_16x16x32_bf16 v[10:13], v[144:147], v[18:21], v[10:13]
	s_waitcnt lgkmcnt(0)
	v_mfma_f32_16x16x32_bf16 v[22:25], v[148:151], v[26:29], v[22:25]
	v_mfma_f32_16x16x32_bf16 v[18:21], v[152:155], v[26:29], v[178:181]
	v_mfma_f32_16x16x32_bf16 v[14:17], v[156:159], v[26:29], v[182:185]
	v_mfma_f32_16x16x32_bf16 v[10:13], v[174:177], v[26:29], v[10:13]
	s_nop 7
	v_cndmask_b32_e64 v26, 0, 1, s[36:37]
	v_cmp_ne_u32_e64 s[58:59], 1, v26
	s_cbranch_vccnz .LBB0_459
	v_add_u32_e32 v28, 0, v59
	v_cvt_pk_bf16_f32 v26, v22, v23
	v_add_u32_e32 v28, 0x21000, v28
	v_cvt_pk_bf16_f32 v27, v24, v25
	ds_write_b64 v28, v[26:27]
	v_cvt_pk_bf16_f32 v26, v18, v19
	v_cvt_pk_bf16_f32 v27, v20, v21
	ds_write_b64 v28, v[26:27] offset:8
	v_cvt_pk_bf16_f32 v26, v14, v15
	v_cvt_pk_bf16_f32 v27, v16, v17
	ds_write_b64 v28, v[26:27] offset:16
	v_cvt_pk_bf16_f32 v26, v10, v11
	v_cvt_pk_bf16_f32 v27, v12, v13
	ds_write_b64 v28, v[26:27] offset:24
	v_add_u32_e32 v26, 0, v57
	v_add_u32_e32 v26, 0x20800, v26
	ds_write_b64 v26, v[32:33]

; #define LAS __attribute__((address_space(3)))
; #define MFMA16(a, b, c) __builtin_amdgcn_mfma_f32_16x16x32_bf16((a), (b), (c), 0, 0, 0)
; __device__ __forceinline__ int att_fk(int key) { return ((key >> 3) & 3) + 4 * ((key >> 1) & 1); }
; #define ATT_BAR() do { asm volatile("s_waitcnt lgkmcnt(0)" ::: "memory"); __builtin_amdgcn_s_barrier(); asm volatile("" ::: "memory"); } while (0)
; __device__ __forceinline__ void attn_phase(const bf16_t* Q, const bf16_t* Kb, const bf16_t* VTa, const float* rpb, bf16_t* Y, LAS unsigned char* lds, int bx, int G, int tid, int wave, int lane) {
;     ...
;         for (int n = 0; n < 8; ++n) {
;             const int r = r0 + n, rs = min(max(r - 4, 0), 120);
;             const bool has_next = n < 7; const int rsn = min(max(r + 1 - 4, 0), 120); const bool newrow = has_next && (rsn != rs);
;             asm volatile("s_waitcnt vmcnt(1)" ::: "memory");
;             ATT_BAR();
;             f32x4 s[4][2];
;             float mx = -3.0e38f;
; #pragma unroll
;             for (int ii = 0; ii < 4; ++ii) {
;                 const int i = 4 * hf + ii, dr = rs + i - r + 7;
;                 float bia[8];
; #pragma unroll
;                 for (int j = 0; j < 8; ++j) bia[j] = rl[((unsigned)(j - wlo) < (unsigned)wwd) ? dr * 31 + dci0 + j : 480];
; #pragma unroll
;                 for (int ta = 0; ta < 2; ++ta) {
;                     const int key = cs + 8 * (fr >> 2) + 4 * ta + (fr & 3), fk = att_fk(key);
;                     const LAS unsigned char* kp = KL + ((rs + i) & 7) * 8192 + key * 128;
;                     const bf16x8 kf0 = *(const LAS bf16x8*)(kp + ((fq ^ fk) << 4)), kf1 = *(const LAS bf16x8*)(kp + (((4 + fq) ^ fk) << 4));
;                     f32x4 a = {0.f, 0.f, 0.f, 0.f};
;                     a = MFMA16(kf0, qf0, a); a = MFMA16(kf1, qf1, a);
; #pragma unroll
;                     for (int idx = 0; idx < 4; ++idx) { a[idx] += bia[4 * ta + idx]; mx = fmaxf(mx, a[idx]); }
;                     s[ii][ta] = a;
;                 }
;             }
.LBB0_465:
	s_or_b32 s20, s93, 7
	s_max_i32 s30, s20, 4
	s_add_i32 s30, s30, -4
	s_min_u32 s30, s30, 0x78
	s_add_i32 s31, s30, s85
	s_sub_i32 s60, s31, s20
	s_lshl_b32 s31, s31, 13
	v_mad_u64_u32 v[10:11], s[60:61], s60, 31, v[46:47]
	s_and_b32 s31, s31, 0xe000
	s_waitcnt vmcnt(1)
	v_cndmask_b32_e64 v11, v245, v10, s[40:41]
	v_add_u32_e32 v14, s31, v61
	s_waitcnt lgkmcnt(0)
	s_barrier
	v_lshl_add_u32 v11, v11, 2, s84
	v_add_u32_e32 v27, v14, v55
	ds_read_b32 v18, v11
	v_add_u32_e32 v26, v14, v41
	ds_read_b128 v[14:17], v27
	v_add_u32_e32 v11, 1, v10
	v_cndmask_b32_e64 v11, v245, v11, s[42:43]
	v_lshl_add_u32 v11, v11, 2, s84
	ds_read_b32 v19, v11
	v_add_u32_e32 v11, 2, v10
	v_cndmask_b32_e64 v11, v245, v11, s[44:45]
	v_lshl_add_u32 v11, v11, 2, s84
	ds_read_b32 v20, v11
	v_add_u32_e32 v11, 3, v10
	v_cndmask_b32_e64 v11, v245, v11, s[46:47]
	v_lshl_add_u32 v11, v11, 2, s84
	ds_read_b32 v21, v11
	v_add_u32_e32 v11, 4, v10
	v_cndmask_b32_e64 v11, v245, v11, s[48:49]
	v_lshl_add_u32 v11, v11, 2, s84
	ds_read_b32 v22, v11
	v_add_u32_e32 v11, 5, v10
	v_cndmask_b32_e64 v11, v245, v11, s[50:51]
	v_lshl_add_u32 v11, v11, 2, s84
	ds_read_b32 v23, v11
	v_add_u32_e32 v11, 6, v10
	v_add_u32_e32 v10, 7, v10
	v_cndmask_b32_e64 v11, v245, v11, s[52:53]
	v_cndmask_b32_e64 v10, v245, v10, s[54:55]
	v_lshl_add_u32 v11, v11, 2, s84
	v_lshl_add_u32 v10, v10, 2, s84
	ds_read_b32 v24, v11
	ds_read_b32 v25, v10
	ds_read_b128 v[10:13], v26
	s_waitcnt vmcnt(0) lgkmcnt(0)
	v_mfma_f32_16x16x32_bf16 v[10:13], v[10:13], v[6:9], 0
	s_add_i32 s31, s30, s89
	s_sub_i32 s60, s31, s20
	s_lshl_b32 s31, s31, 13
	v_mfma_f32_16x16x32_bf16 v[14:17], v[14:17], v[2:5], v[10:13]
	s_and_b32 s31, s31, 0xe000
	s_nop 6
	v_add_f32_e32 v13, v18, v14
	v_add_f32_e32 v12, v19, v15
	v_max3_f32 v14, v13, s6, v12
	v_add_f32_e32 v11, v20, v16
	v_add_f32_e32 v10, v21, v17
	v_max3_f32 v28, v14, v11, v10
	ds_read_b128 v[14:17], v26 offset:512
	ds_read_b128 v[18:21], v27 offset:512
	s_waitcnt lgkmcnt(1)
	v_mfma_f32_16x16x32_bf16 v[14:17], v[14:17], v[6:9], 0
	s_waitcnt lgkmcnt(0)
	v_mfma_f32_16x16x32_bf16 v[18:21], v[18:21], v[2:5], v[14:17]
	s_nop 7
	v_add_f32_e32 v17, v22, v18
	v_add_f32_e32 v16, v23, v19
	v_max3_f32 v18, v28, v17, v16
	v_add_f32_e32 v15, v24, v20
	v_add_f32_e32 v14, v25, v21
	v_max3_f32 v26, v18, v15, v14
	v_mad_u64_u32 v[18:19], s[60:61], s60, 31, v[46:47]
	v_cndmask_b32_e64 v19, v245, v18, s[40:41]
	v_add_u32_e32 v22, s31, v61
	v_lshl_add_u32 v19, v19, 2, s84
	v_add_u32_e32 v63, v22, v55
	ds_read_b32 v27, v19
	v_add_u32_e32 v37, v22, v41
	ds_read_b128 v[22:25], v63
	v_add_u32_e32 v19, 1, v18
	v_cndmask_b32_e64 v19, v245, v19, s[42:43]
	v_lshl_add_u32 v19, v19, 2, s84
	ds_read_b32 v28, v19
	v_add_u32_e32 v19, 2, v18
	v_cndmask_b32_e64 v19, v245, v19, s[44:45]
	v_lshl_add_u32 v19, v19, 2, s84
	ds_read_b32 v29, v19
	v_add_u32_e32 v19, 3, v18
	v_cndmask_b32_e64 v19, v245, v19, s[46:47]
	v_lshl_add_u32 v19, v19, 2, s84
	ds_read_b32 v30, v19
	v_add_u32_e32 v19, 4, v18
	v_cndmask_b32_e64 v19, v245, v19, s[48:49]
	v_lshl_add_u32 v19, v19, 2, s84
	ds_read_b32 v32, v19
	v_add_u32_e32 v19, 5, v18
	v_cndmask_b32_e64 v19, v245, v19, s[50:51]
	v_lshl_add_u32 v19, v19, 2, s84
	ds_read_b32 v33, v19
	v_add_u32_e32 v19, 6, v18
	v_add_u32_e32 v18, 7, v18
	v_cndmask_b32_e64 v19, v245, v19, s[52:53]
	v_cndmask_b32_e64 v18, v245, v18, s[54:55]
	v_lshl_add_u32 v19, v19, 2, s84
	v_lshl_add_u32 v18, v18, 2, s84
	ds_read_b32 v35, v19
	ds_read_b32 v36, v18
	ds_read_b128 v[18:21], v37
	s_waitcnt lgkmcnt(0)
	v_mfma_f32_16x16x32_bf16 v[18:21], v[18:21], v[6:9], 0
	s_add_i32 s31, s30, s90
	s_sub_i32 s60, s31, s20
	s_lshl_b32 s31, s31, 13
	v_mfma_f32_16x16x32_bf16 v[22:25], v[22:25], v[2:5], v[18:21]
	s_and_b32 s31, s31, 0xe000
	v_add_u32_e32 v73, s31, v61
	v_add_u32_e32 v75, v73, v41
	v_add_u32_e32 v73, v73, v55
	s_add_i32 s31, s30, s91
	s_nop 2
	v_add_f32_e32 v22, v27, v22
	v_add_f32_e32 v21, v28, v23
	v_max3_f32 v18, v26, v22, v21
	v_add_f32_e32 v20, v29, v24
	v_add_f32_e32 v19, v30, v25
	ds_read_b128 v[24:27], v37 offset:512
	ds_read_b128 v[92:95], v63 offset:512
	s_waitcnt lgkmcnt(1)
	v_mfma_f32_16x16x32_bf16 v[24:27], v[24:27], v[6:9], 0
	v_max3_f32 v18, v18, v20, v19
	s_waitcnt lgkmcnt(0)
	v_mfma_f32_16x16x32_bf16 v[24:27], v[92:95], v[2:5], v[24:27]
	ds_read_b128 v[92:95], v73
	s_nop 6
	v_add_f32_e32 v23, v32, v24
	v_add_f32_e32 v28, v33, v25
	v_mad_u64_u32 v[24:25], s[60:61], s60, 31, v[46:47]
	v_cndmask_b32_e64 v25, v245, v24, s[40:41]
	v_lshl_add_u32 v25, v25, 2, s84
	ds_read_b32 v32, v25
	v_add_u32_e32 v25, 1, v24
	v_cndmask_b32_e64 v25, v245, v25, s[42:43]
	v_lshl_add_u32 v25, v25, 2, s84
	ds_read_b32 v33, v25
	v_add_u32_e32 v25, 2, v24
	v_cndmask_b32_e64 v25, v245, v25, s[44:45]
	v_lshl_add_u32 v25, v25, 2, s84
	v_add_f32_e32 v29, v35, v26
	ds_read_b32 v35, v25
	v_add_u32_e32 v25, 3, v24
	v_cndmask_b32_e64 v25, v245, v25, s[46:47]
	v_lshl_add_u32 v25, v25, 2, s84
	v_add_f32_e32 v30, v36, v27
	ds_read_b32 v36, v25
	v_add_u32_e32 v25, 4, v24
	v_cndmask_b32_e64 v25, v245, v25, s[48:49]
	v_lshl_add_u32 v25, v25, 2, s84
	ds_read_b32 v37, v25
	v_add_u32_e32 v25, 5, v24
	v_cndmask_b32_e64 v25, v245, v25, s[50:51]
	v_lshl_add_u32 v25, v25, 2, s84
	ds_read_b32 v63, v25
	v_add_u32_e32 v25, 6, v24
	v_add_u32_e32 v24, 7, v24
	v_cndmask_b32_e64 v25, v245, v25, s[52:53]
	v_cndmask_b32_e64 v24, v245, v24, s[54:55]
	v_lshl_add_u32 v25, v25, 2, s84
	v_lshl_add_u32 v24, v24, 2, s84
	ds_read_b32 v65, v25
	ds_read_b32 v71, v24
	ds_read_b128 v[24:27], v75
	s_waitcnt lgkmcnt(0)
; #define LAS __attribute__((address_space(3)))
; __device__ __forceinline__ float fast_exp2(float x) { return __builtin_amdgcn_exp2f(x); }
; __device__ __forceinline__ void attn_phase(const bf16_t* Q, const bf16_t* Kb, const bf16_t* VTa, const float* rpb, bf16_t* Y, LAS unsigned char* lds, int bx, int G, int tid, int wave, int lane) {
;     ...
; #pragma unroll
;             for (int ii = 0; ii < 4; ++ii) {
;                 const int i = 4 * hf + ii, dr = rs + i - r + 7;
;                 float bia[8];
; #pragma unroll
;                 for (int j = 0; j < 8; ++j) bia[j] = rl[((unsigned)(j - wlo) < (unsigned)wwd) ? dr * 31 + dci0 + j : 480];
; #pragma unroll
;                 for (int ta = 0; ta < 2; ++ta) {
;                     const int key = cs + 8 * (fr >> 2) + 4 * ta + (fr & 3), fk = att_fk(key);
;                     const LAS unsigned char* kp = KL + ((rs + i) & 7) * 8192 + key * 128;
;                     const bf16x8 kf0 = *(const LAS bf16x8*)(kp + ((fq ^ fk) << 4)), kf1 = *(const LAS bf16x8*)(kp + (((4 + fq) ^ fk) << 4));
;                     f32x4 a = {0.f, 0.f, 0.f, 0.f};
;                     a = MFMA16(kf0, qf0, a); a = MFMA16(kf1, qf1, a);
; #pragma unroll
;                     for (int idx = 0; idx < 4; ++idx) { a[idx] += bia[4 * ta + idx]; mx = fmaxf(mx, a[idx]); }
;                     s[ii][ta] = a;
;                 }
;             }
;             ATT_BAR();
;             SCHED_FENCE();
;             if (newrow) ATT_K_PIECE(h, rs + 8, wave);
;             SCHED_FENCE();
;             if (has_next) { const bf16_t* qp = Q + (size_t)((r + 1) * 64 + c) * 1024 + h * 64 + 8 * fq; qf0 = *(const bf16x8*)qp; qf1 = *(const bf16x8*)(qp + 32); }
;             SCHED_FENCE();
;             mx = fmaxf(mx, __shfl_xor(mx, 16)); mx = fmaxf(mx, __shfl_xor(mx, 32));
;             float l = 0.f;
;             bf16x8 pb[4];
; #pragma unroll
;             for (int ii = 0; ii < 4; ++ii) {
;                 f32x4 p0, p1;
; #pragma unroll
;                 for (int idx = 0; idx < 4; ++idx) { p0[idx] = fast_exp2((s[ii][0][idx] - mx) * 1.4426950409f); p1[idx] = fast_exp2((s[ii][1][idx] - mx) * 1.4426950409f); }
;                 l += (p0[0] + p0[1]) + (p0[2] + p0[3]) + (p1[0] + p1[1]) + (p1[2] + p1[3]);
;                 const u32x4 pw = pack8(p0, p1); pb[ii] = __builtin_bit_cast(bf16x8, pw);
;             }
;             l += __shfl_xor(l, 16); l += __shfl_xor(l, 32);
	v_mfma_f32_16x16x32_bf16 v[24:27], v[24:27], v[6:9], 0
	s_sub_i32 s60, s31, s20
	s_lshl_b32 s31, s31, 13
	s_and_b32 s31, s31, 0xe000
	v_mfma_f32_16x16x32_bf16 v[24:27], v[92:95], v[2:5], v[24:27]
	v_add_u32_e32 v89, s31, v61
	v_add_u32_e32 v91, v89, v41
	v_add_u32_e32 v89, v89, v55
	v_max3_f32 v18, v18, v23, v28
	v_max3_f32 v18, v18, v29, v30
	s_nop 2
	v_add_f32_e32 v32, v32, v24
	v_add_f32_e32 v33, v33, v25
	v_add_f32_e32 v35, v35, v26
	v_add_f32_e32 v36, v36, v27
	ds_read_b128 v[24:27], v75 offset:512
	ds_read_b128 v[92:95], v73 offset:512
	s_waitcnt lgkmcnt(1)
	v_mfma_f32_16x16x32_bf16 v[24:27], v[24:27], v[6:9], 0
	v_max3_f32 v18, v18, v32, v33
	v_max3_f32 v18, v18, v35, v36
	s_waitcnt lgkmcnt(0)
	v_mfma_f32_16x16x32_bf16 v[24:27], v[92:95], v[2:5], v[24:27]
	ds_read_b128 v[92:95], v89
	s_nop 6
	v_add_f32_e32 v37, v37, v24
	v_add_f32_e32 v63, v63, v25
	v_mad_u64_u32 v[24:25], s[60:61], s60, 31, v[46:47]
	v_cndmask_b32_e64 v25, v245, v24, s[40:41]
	v_lshl_add_u32 v25, v25, 2, s84
	ds_read_b32 v73, v25
	v_add_u32_e32 v25, 1, v24
	v_cndmask_b32_e64 v25, v245, v25, s[42:43]
	v_lshl_add_u32 v25, v25, 2, s84
	ds_read_b32 v75, v25
	v_add_u32_e32 v25, 2, v24
	v_cndmask_b32_e64 v25, v245, v25, s[44:45]
	v_lshl_add_u32 v25, v25, 2, s84
	ds_read_b32 v77, v25
	v_add_u32_e32 v25, 3, v24
	v_cndmask_b32_e64 v25, v245, v25, s[46:47]
	v_lshl_add_u32 v25, v25, 2, s84
	ds_read_b32 v79, v25
	v_add_u32_e32 v25, 4, v24
	v_cndmask_b32_e64 v25, v245, v25, s[48:49]
	v_lshl_add_u32 v25, v25, 2, s84
	ds_read_b32 v81, v25
	v_add_u32_e32 v25, 5, v24
	v_cndmask_b32_e64 v25, v245, v25, s[50:51]
	v_lshl_add_u32 v25, v25, 2, s84
	ds_read_b32 v83, v25
	v_add_u32_e32 v25, 6, v24
	v_add_u32_e32 v24, 7, v24
	v_cndmask_b32_e64 v25, v245, v25, s[52:53]
	v_cndmask_b32_e64 v24, v245, v24, s[54:55]
	v_lshl_add_u32 v25, v25, 2, s84
	v_lshl_add_u32 v24, v24, 2, s84
	v_add_f32_e32 v65, v65, v26
	v_add_f32_e32 v71, v71, v27
	ds_read_b32 v85, v25
	ds_read_b32 v87, v24
	ds_read_b128 v[24:27], v91
	s_waitcnt lgkmcnt(0)
	v_mfma_f32_16x16x32_bf16 v[24:27], v[24:27], v[6:9], 0
	v_max3_f32 v18, v18, v37, v63
	v_max3_f32 v18, v18, v65, v71
	v_mfma_f32_16x16x32_bf16 v[24:27], v[92:95], v[2:5], v[24:27]
	s_nop 7
	v_add_f32_e32 v73, v73, v24
	v_add_f32_e32 v75, v75, v25
	v_add_f32_e32 v77, v77, v26
	v_add_f32_e32 v79, v79, v27
	ds_read_b128 v[24:27], v91 offset:512
	ds_read_b128 v[92:95], v89 offset:512
	s_waitcnt lgkmcnt(1)
	v_mfma_f32_16x16x32_bf16 v[6:9], v[24:27], v[6:9], 0
	v_max3_f32 v18, v18, v73, v75
	v_max3_f32 v18, v18, v77, v79
	s_waitcnt lgkmcnt(0)
	s_waitcnt lgkmcnt(0)
	v_mfma_f32_16x16x32_bf16 v[2:5], v[92:95], v[2:5], v[6:9]
	s_barrier
	s_nop 6
	v_add_f32_e32 v24, v81, v2
	v_add_f32_e32 v25, v83, v3
	v_max3_f32 v2, v18, v24, v25
	v_add_f32_e32 v26, v85, v4
	v_add_f32_e32 v27, v87, v5
	v_max3_f32 v2, v2, v26, v27
	ds_bpermute_b32 v3, v31, v2
	s_waitcnt lgkmcnt(0)
	v_max_f32_e32 v3, v3, v3
	v_max_f32_e32 v2, v2, v3
	ds_bpermute_b32 v3, v34, v2
	s_waitcnt lgkmcnt(0)
	v_max_f32_e32 v3, v3, v3
	v_max_f32_e32 v18, v2, v3
	v_sub_f32_e32 v3, v17, v18
	v_sub_f32_e32 v4, v12, v18
	v_sub_f32_e32 v5, v16, v18
	v_mul_f32_e32 v3, 0x3fb8aa3b, v3
	v_mul_f32_e32 v4, 0x3fb8aa3b, v4
	v_mul_f32_e32 v5, 0x3fb8aa3b, v5
	v_sub_f32_e32 v2, v13, v18
	v_exp_f32_e32 v6, v3
	v_exp_f32_e32 v3, v4
	v_exp_f32_e32 v4, v5
	v_sub_f32_e32 v5, v11, v18
	v_sub_f32_e32 v8, v10, v18
	v_mul_f32_e32 v2, 0x3fb8aa3b, v2
	v_mul_f32_e32 v5, 0x3fb8aa3b, v5
	v_mul_f32_e32 v8, 0x3fb8aa3b, v8
	v_exp_f32_e32 v2, v2
	v_exp_f32_e32 v5, v5
	v_sub_f32_e32 v7, v15, v18
	v_exp_f32_e32 v8, v8
	v_sub_f32_e32 v9, v14, v18
	v_mul_f32_e32 v7, 0x3fb8aa3b, v7
	v_mul_f32_e32 v9, 0x3fb8aa3b, v9
	v_exp_f32_e32 v7, v7
	v_exp_f32_e32 v9, v9
	v_add_f32_e32 v10, v2, v3
	v_add_f32_e32 v11, v5, v8
	v_add_f32_e32 v10, v10, v11
	v_add_f32_e32 v11, v6, v4
	v_add_f32_e32 v10, v11, v10
	v_add_f32_e32 v11, v7, v9
	v_cvt_pk_bf16_f32 v2, v2, v3
	v_cvt_pk_bf16_f32 v3, v5, v8
	v_cvt_pk_bf16_f32 v4, v6, v4
	v_cvt_pk_bf16_f32 v5, v7, v9
	v_sub_f32_e32 v7, v23, v18
	v_mul_f32_e32 v7, 0x3fb8aa3b, v7
	v_add_f32_e32 v10, v11, v10
	v_sub_f32_e32 v6, v22, v18
	v_exp_f32_e32 v8, v7
	v_sub_f32_e32 v7, v21, v18
	v_sub_f32_e32 v11, v20, v18
	v_sub_f32_e32 v13, v19, v18
	v_mul_f32_e32 v6, 0x3fb8aa3b, v6
	v_mul_f32_e32 v7, 0x3fb8aa3b, v7
	v_sub_f32_e32 v9, v28, v18
	v_mul_f32_e32 v11, 0x3fb8aa3b, v11
	v_mul_f32_e32 v13, 0x3fb8aa3b, v13
	v_exp_f32_e32 v6, v6
	v_exp_f32_e32 v7, v7
	v_mul_f32_e32 v9, 0x3fb8aa3b, v9
	v_exp_f32_e32 v11, v11
	v_sub_f32_e32 v12, v29, v18
	v_exp_f32_e32 v13, v13
	v_sub_f32_e32 v14, v30, v18
	v_exp_f32_e32 v9, v9
	v_mul_f32_e32 v12, 0x3fb8aa3b, v12
	v_mul_f32_e32 v14, 0x3fb8aa3b, v14
	v_exp_f32_e32 v12, v12
	v_exp_f32_e32 v14, v14
	v_add_f32_e32 v15, v6, v7
	v_add_f32_e32 v16, v11, v13
	v_add_f32_e32 v15, v15, v16
	v_add_f32_e32 v16, v8, v9
	v_add_f32_e32 v15, v16, v15
	v_add_f32_e32 v16, v12, v14
	v_add_f32_e32 v10, 0, v10
	v_add_f32_e32 v15, v16, v15
	v_add_f32_e32 v10, v15, v10
	v_cvt_pk_bf16_f32 v6, v6, v7
	v_cvt_pk_bf16_f32 v7, v11, v13
	v_sub_f32_e32 v11, v32, v18
	v_sub_f32_e32 v13, v33, v18
; #define LAS __attribute__((address_space(3)))
; __device__ __forceinline__ unsigned cvt_pk_bf16(float lo, float hi) { unsigned r; asm volatile("v_cvt_pk_bf16_f32 %0, %1, %2" : "=v"(r) : "v"(lo), "v"(hi)); return r; }
; __device__ __forceinline__ float fast_exp2(float x) { return __builtin_amdgcn_exp2f(x); }
; __device__ __forceinline__ void attn_phase(const bf16_t* Q, const bf16_t* Kb, const bf16_t* VTa, const float* rpb, bf16_t* Y, LAS unsigned char* lds, int bx, int G, int tid, int wave, int lane) {
;     ...
;             float l = 0.f;
;             bf16x8 pb[4];
; #pragma unroll
;             for (int ii = 0; ii < 4; ++ii) {
;                 f32x4 p0, p1;
; #pragma unroll
;                 for (int idx = 0; idx < 4; ++idx) { p0[idx] = fast_exp2((s[ii][0][idx] - mx) * 1.4426950409f); p1[idx] = fast_exp2((s[ii][1][idx] - mx) * 1.4426950409f); }
;                 l += (p0[0] + p0[1]) + (p0[2] + p0[3]) + (p1[0] + p1[1]) + (p1[2] + p1[3]);
;                 const u32x4 pw = pack8(p0, p1); pb[ii] = __builtin_bit_cast(bf16x8, pw);
;             }
;             l += __shfl_xor(l, 16); l += __shfl_xor(l, 32);
;             SCHED_FENCE();
;             if (newrow) asm volatile("s_waitcnt vmcnt(3)" ::: "memory"); else if (has_next) asm volatile("s_waitcnt vmcnt(2)" ::: "memory"); else asm volatile("s_waitcnt vmcnt(0)" ::: "memory");
;             ATT_BAR();
;             f32x4 o[4];
; #pragma unroll
;             for (int dt = 0; dt < 4; ++dt) o[dt] = (f32x4){0.f, 0.f, 0.f, 0.f};
; #pragma unroll
;             for (int ii = 0; ii < 4; ++ii) {
;                 const int i = 4 * hf + ii;
; #pragma unroll
;                 for (int dt = 0; dt < 4; ++dt) { const int dh = 16 * dt + fr;
;                     const bf16x8 vf = *(const LAS bf16x8*)(VL + ((rs + i) & 7) * 8192 + dh * 128 + ((((cs >> 3) + fq) ^ att_fv(dh)) << 4));
;                     o[dt] = MFMA16(vf, pb[ii], o[dt]); }
;             }
;             LAS float* ml = (LAS float*)(lds + 131072 + 2048) + (size_t)(g * 64 + lane) * 2;
;             LAS u32x2* ol = (LAS u32x2*)(lds + 131072 + 4096) + (size_t)(g * 64 + lane) * 4;
;             if (hf == 1) {
; #pragma unroll
;                 for (int dt = 0; dt < 4; ++dt) { u32x2 w; w.x = cvt_pk_bf16(o[dt][0], o[dt][1]); w.y = cvt_pk_bf16(o[dt][2], o[dt][3]); ol[dt] = w; }
;                 ml[0] = mx; ml[1] = l;
	v_sub_f32_e32 v15, v35, v18
	v_sub_f32_e32 v17, v36, v18
	v_cvt_pk_bf16_f32 v8, v8, v9
	v_cvt_pk_bf16_f32 v9, v12, v14
	v_mul_f32_e32 v11, 0x3fb8aa3b, v11
	v_sub_f32_e32 v12, v37, v18
	v_mul_f32_e32 v13, 0x3fb8aa3b, v13
	v_sub_f32_e32 v14, v63, v18
	v_mul_f32_e32 v15, 0x3fb8aa3b, v15
	v_mul_f32_e32 v17, 0x3fb8aa3b, v17
	v_exp_f32_e32 v11, v11
	v_mul_f32_e32 v12, 0x3fb8aa3b, v12
	v_exp_f32_e32 v13, v13
	v_mul_f32_e32 v14, 0x3fb8aa3b, v14
	v_exp_f32_e32 v15, v15
	v_sub_f32_e32 v16, v65, v18
	v_exp_f32_e32 v17, v17
	v_sub_f32_e32 v19, v71, v18
	v_exp_f32_e32 v12, v12
	v_exp_f32_e32 v14, v14
	v_mul_f32_e32 v16, 0x3fb8aa3b, v16
	v_mul_f32_e32 v19, 0x3fb8aa3b, v19
	v_exp_f32_e32 v16, v16
	v_exp_f32_e32 v19, v19
	v_add_f32_e32 v20, v11, v13
	v_add_f32_e32 v21, v15, v17
	v_add_f32_e32 v20, v20, v21
	v_add_f32_e32 v21, v12, v14
	v_add_f32_e32 v20, v21, v20
	v_add_f32_e32 v21, v16, v19
	v_add_f32_e32 v20, v21, v20
	v_sub_f32_e32 v21, v24, v18
	v_mul_f32_e32 v21, 0x3fb8aa3b, v21
	v_add_f32_e32 v10, v20, v10
	v_sub_f32_e32 v20, v73, v18
	v_exp_f32_e32 v22, v21
	v_sub_f32_e32 v21, v75, v18
	v_sub_f32_e32 v23, v25, v18
	v_sub_f32_e32 v24, v77, v18
	v_sub_f32_e32 v25, v26, v18
	v_sub_f32_e32 v26, v79, v18
	v_mul_f32_e32 v20, 0x3fb8aa3b, v20
	v_mul_f32_e32 v21, 0x3fb8aa3b, v21
	v_mul_f32_e32 v24, 0x3fb8aa3b, v24
	v_mul_f32_e32 v26, 0x3fb8aa3b, v26
	v_exp_f32_e32 v20, v20
	v_exp_f32_e32 v21, v21
	v_mul_f32_e32 v23, 0x3fb8aa3b, v23
	v_exp_f32_e32 v24, v24
	v_exp_f32_e32 v26, v26
	v_sub_f32_e32 v27, v27, v18
	v_exp_f32_e32 v23, v23
	v_mul_f32_e32 v25, 0x3fb8aa3b, v25
	v_mul_f32_e32 v27, 0x3fb8aa3b, v27
	v_exp_f32_e32 v25, v25
	v_exp_f32_e32 v27, v27
	v_add_f32_e32 v28, v20, v21
	v_add_f32_e32 v29, v24, v26
	v_add_f32_e32 v28, v28, v29
	v_add_f32_e32 v29, v22, v23
	v_add_f32_e32 v28, v29, v28
	v_add_f32_e32 v29, v25, v27
	v_add_f32_e32 v28, v29, v28
	v_add_f32_e32 v28, v28, v10
	ds_bpermute_b32 v29, v31, v28
	v_cvt_pk_bf16_f32 v10, v11, v13
	v_cvt_pk_bf16_f32 v11, v15, v17
	v_cvt_pk_bf16_f32 v12, v12, v14
	v_cvt_pk_bf16_f32 v13, v16, v19
	s_waitcnt lgkmcnt(0)
	v_add_f32_e32 v14, v28, v29
	ds_bpermute_b32 v15, v34, v14
	v_cvt_pk_bf16_f32 v20, v20, v21
	v_cvt_pk_bf16_f32 v21, v24, v26
	v_cvt_pk_bf16_f32 v22, v22, v23
	v_cvt_pk_bf16_f32 v23, v25, v27
	s_waitcnt lgkmcnt(0)
	v_add_f32_e32 v19, v14, v15
	s_or_b32 s30, s30, s87
	s_lshl_b32 s30, s30, 13
	s_waitcnt vmcnt(0)
	s_and_b32 s31, s30, 0xe000
	s_waitcnt lgkmcnt(0)
	s_barrier
	v_add_u32_e32 v32, s31, v49
	s_add_i32 s31, s30, 0x2000
	s_and_b32 s31, s31, 0xe000
	v_add_u32_e32 v33, s31, v49
	s_add_i32 s31, s30, 0x4000
	s_and_b32 s31, s31, 0xe000
	v_add_u32_e32 v34, s31, v49
	s_addk_i32 s30, 0x6000
	s_and_b32 s30, s30, 0xe000
	v_add_u32_e32 v35, s30, v49
	s_and_b64 vcc, exec, s[58:59]
	ds_read_b128 v[108:111], v32
	ds_read_b128 v[112:115], v32 offset:2048
	ds_read_b128 v[116:119], v32 offset:4096
	ds_read_b128 v[120:123], v32 offset:6144
	ds_read_b128 v[124:127], v33
	ds_read_b128 v[128:131], v33 offset:2048
	ds_read_b128 v[132:135], v33 offset:4096
	ds_read_b128 v[136:139], v33 offset:6144
	ds_read_b128 v[140:143], v34
	ds_read_b128 v[144:147], v34 offset:2048
	ds_read_b128 v[148:151], v34 offset:4096
	ds_read_b128 v[152:155], v34 offset:6144
	ds_read_b128 v[174:177], v35
	ds_read_b128 v[178:181], v35 offset:2048
	ds_read_b128 v[182:185], v35 offset:4096
	ds_read_b128 v[186:189], v35 offset:6144
	s_waitcnt lgkmcnt(12)
	v_mfma_f32_16x16x32_bf16 v[14:17], v[108:111], v[2:5], 0
	v_mfma_f32_16x16x32_bf16 v[24:27], v[112:115], v[2:5], 0
	v_mfma_f32_16x16x32_bf16 v[28:31], v[116:119], v[2:5], 0
	v_mfma_f32_16x16x32_bf16 v[2:5], v[120:123], v[2:5], 0
	s_waitcnt lgkmcnt(8)
	v_mfma_f32_16x16x32_bf16 v[14:17], v[124:127], v[6:9], v[14:17]
	v_mfma_f32_16x16x32_bf16 v[24:27], v[128:131], v[6:9], v[24:27]
	v_mfma_f32_16x16x32_bf16 v[28:31], v[132:135], v[6:9], v[28:31]
	v_mfma_f32_16x16x32_bf16 v[2:5], v[136:139], v[6:9], v[2:5]
	s_waitcnt lgkmcnt(4)
	v_mfma_f32_16x16x32_bf16 v[14:17], v[140:143], v[10:13], v[14:17]
	v_mfma_f32_16x16x32_bf16 v[24:27], v[144:147], v[10:13], v[24:27]
	v_mfma_f32_16x16x32_bf16 v[28:31], v[148:151], v[10:13], v[28:31]
	v_mfma_f32_16x16x32_bf16 v[2:5], v[152:155], v[10:13], v[2:5]
	s_waitcnt lgkmcnt(0)
	v_mfma_f32_16x16x32_bf16 v[14:17], v[174:177], v[20:23], v[14:17]
	v_mfma_f32_16x16x32_bf16 v[10:13], v[178:181], v[20:23], v[24:27]
	v_mfma_f32_16x16x32_bf16 v[6:9], v[182:185], v[20:23], v[28:31]
	v_mfma_f32_16x16x32_bf16 v[2:5], v[186:189], v[20:23], v[2:5]
	s_nop 7
	v_add_u32_e32 v20, 0, v59
	v_add_u32_e32 v21, 0, v57
	v_add_u32_e32 v20, 0x21000, v20
	v_add_u32_e32 v21, 0x20800, v21
	s_cbranch_vccnz .LBB0_467
	v_cvt_pk_bf16_f32 v22, v14, v15
	v_cvt_pk_bf16_f32 v23, v16, v17
	ds_write_b64 v20, v[22:23]
	v_cvt_pk_bf16_f32 v22, v10, v11
	v_cvt_pk_bf16_f32 v23, v12, v13
	ds_write_b64 v20, v[22:23] offset:8
	v_cvt_pk_bf16_f32 v22, v6, v7
	v_cvt_pk_bf16_f32 v23, v8, v9
	ds_write_b64 v20, v[22:23] offset:16
	v_cvt_pk_bf16_f32 v22, v2, v3
	v_cvt_pk_bf16_f32 v23, v4, v5
	ds_write_b64 v20, v[22:23] offset:24
	ds_write_b64 v21, v[18:19]
